# final RMSNorm pass: row stores issued after the next row's sum-of-squares loads (outputs in spare registers) + out_proj epilogue early residual loads + in_proj epilogue wait fixes
# speedup vs baseline: 1.0107x; 1.0087x over previous
;     __device__ __forceinline__ void after(f32x4 (&acc)[2][2][4][2], const Unit& u, int wr, int wc, int fr, int fq) const {
;     ...
; #pragma unroll
;         for (int ai = 0; ai < 2; ++ai)
; #pragma unroll
;             for (int m = 0; m < 4; ++m) {
;                 const int row = 256 * u.pm + 128 * ai + 64 * wr + 16 * m + fr;
;                 const f32x4* sp = (const f32x4*)(SSQ + row * 16);
;                 const f32x4 s0 = sp[0], s1 = sp[1], s2 = sp[2], s3 = sp[3];
;                 const float tot = ((s0[0] + s0[1]) + (s0[2] + s0[3])) + ((s1[0] + s1[1]) + (s1[2] + s1[3])) + ((s2[0] + s2[1]) + (s2[2] + s2[3])) + ((s3[0] + s3[1]) + (s3[2] + s3[3]));
;                 const float rinv = 1.0f / sqrtf(tot * (1.f / DM) + 1e-6f);
; #pragma unroll
;                 for (int bj = 0; bj < 2; ++bj)
; #pragma unroll
;                     for (int n = 0; n < 2; ++n) {
;                         const int col = 256 * u.pn + 64 * wc + 32 * bj + 8 * fq + 4 * n;
;                         *(f32x4*)(out + (size_t)row * 1024 + col) = acc[ai][bj][m][n] * rinv * gn[bj][n];
;                     }
.LBB0_567:
	s_or_b64 exec, exec, s[2:3]
	s_lshl_b32 s0, s10, 8
	s_ashr_i32 s1, s0, 31
	s_lshl_b64 s[2:3], s[0:1], 2
	s_add_u32 s1, s72, s2
	s_addc_u32 s3, s73, s3
	s_lshl_b32 s2, s11, 2
	s_add_u32 s2, s1, s2
	s_addc_u32 s3, s3, 0
	s_lshl_b32 s1, s8, 8
	s_add_i32 s1, s1, s9
	v_or_b32_e32 v146, s1, v195
	s_waitcnt lgkmcnt(0)
	v_lshlrev_b32_e32 v128, 4, v146
	v_ashrrev_i32_e32 v129, 31, v128
	v_lshl_add_u64 v[128:129], v[128:129], 2, s[6:7]
	s_barrier
	global_load_dwordx4 v[150:153], v[128:129], off
	global_load_dwordx4 v[154:157], v[128:129], off offset:16
	global_load_dwordx4 v[158:161], v[128:129], off offset:32
	global_load_dwordx4 v[162:165], v[128:129], off offset:48
	v_lshlrev_b32_e32 v128, 2, v194
	global_load_dwordx4 v[140:143], v128, s[2:3]
	global_load_dwordx4 v[136:139], v128, s[2:3] offset:16
	global_load_dwordx4 v[132:135], v128, s[2:3] offset:128
	s_nop 0
	global_load_dwordx4 v[128:131], v128, s[2:3] offset:144
	v_ashrrev_i32_e32 v147, 31, v146
	v_mov_b32_e32 v149, 0x358637bd
	v_lshlrev_b64 v[168:169], 12, v[146:147]
	s_mov_b32 s2, 0xf800000
	v_or_b32_e32 v144, s11, v194
	v_or_b32_e32 v144, s0, v144
	v_mov_b32_e32 v148, 0x260
	v_ashrrev_i32_e32 v145, 31, v144
	v_or_b32_e32 v166, 16, v146
	v_lshlrev_b64 v[144:145], 2, v[144:145]
	v_lshlrev_b32_e32 v170, 4, v166
	v_ashrrev_i32_e32 v171, 31, v170
	v_ashrrev_i32_e32 v167, 31, v166
	s_waitcnt vmcnt(7)
	v_mov_b32_e32 v172, v151
	v_mov_b32_e32 v173, v152
	v_mov_b32_e32 v151, v153
	s_waitcnt vmcnt(6)
	v_mov_b32_e32 v152, v155
	v_mov_b32_e32 v153, v156
	v_mov_b32_e32 v155, v157
	v_pk_add_f32 v[150:151], v[172:173], v[150:151]
	v_pk_add_f32 v[152:153], v[152:153], v[154:155]
	v_pk_add_f32 v[150:151], v[150:151], v[150:151] op_sel:[0,1] op_sel_hi:[1,0]
	v_pk_add_f32 v[152:153], v[152:153], v[152:153] op_sel:[0,1] op_sel_hi:[1,0]
	s_waitcnt vmcnt(5)
	v_add_f32_e32 v156, v158, v159
	v_add_f32_e32 v158, v160, v161
	s_waitcnt vmcnt(4)
	v_mov_b32_e32 v157, v164
	v_mov_b32_e32 v159, v165
	v_mov_b32_e32 v151, v162
	v_mov_b32_e32 v153, v163
	v_pk_add_f32 v[154:155], v[156:157], v[158:159]
	v_pk_add_f32 v[150:151], v[150:151], v[152:153]
	s_nop 0
	v_pk_add_f32 v[150:151], v[150:151], v[154:155]
	s_nop 0
	v_add_f32_e32 v147, v150, v151
	v_fmamk_f32 v147, v147, 0x3a800000, v149
	v_mul_f32_e32 v150, 0x4f800000, v147
	v_cmp_gt_f32_e32 vcc, s2, v147
	s_nop 1
	v_cndmask_b32_e32 v147, v147, v150, vcc
	v_sqrt_f32_e32 v152, v147
	v_lshl_add_u64 v[150:151], s[74:75], 0, v[168:169]
	v_lshl_add_u64 v[150:151], v[150:151], 0, v[144:145]
	v_add_u32_e32 v153, -1, v152
	v_add_u32_e32 v154, 1, v152
	v_fma_f32 v155, -v153, v152, v147
	v_fma_f32 v156, -v154, v152, v147
	v_cmp_ge_f32_e64 s[0:1], 0, v155
	s_nop 1
	v_cndmask_b32_e64 v152, v152, v153, s[0:1]
	v_cmp_lt_f32_e64 s[0:1], 0, v156
	s_nop 1
	v_cndmask_b32_e64 v152, v152, v154, s[0:1]
	v_mul_f32_e32 v153, 0x37800000, v152
	v_cndmask_b32_e32 v152, v152, v153, vcc
	v_cmp_class_f32_e32 vcc, v147, v148
	s_nop 1
	v_cndmask_b32_e32 v147, v152, v147, vcc
	v_div_scale_f32 v154, s[0:1], v147, v147, 1.0
	v_rcp_f32_e32 v155, v154
	v_div_scale_f32 v156, vcc, 1.0, v147, 1.0
	v_lshl_add_u64 v[152:153], v[170:171], 2, s[6:7]
	v_fma_f32 v157, -v154, v155, 1.0
	v_fmac_f32_e32 v155, v157, v155
	v_mul_f32_e32 v157, v156, v155
	v_fma_f32 v158, -v154, v157, v156
	v_fmac_f32_e32 v157, v158, v155
	v_fma_f32 v154, -v154, v157, v156
	v_div_fmas_f32 v154, v154, v155, v157
	v_div_fixup_f32 v154, v154, v147, 1.0
	v_pk_mul_f32 v[124:125], v[124:125], v[154:155] op_sel_hi:[1,0]
	v_pk_mul_f32 v[126:127], v[126:127], v[154:155] op_sel_hi:[1,0]
	v_pk_mul_f32 v[120:121], v[120:121], v[154:155] op_sel_hi:[1,0]
	v_pk_mul_f32 v[122:123], v[122:123], v[154:155] op_sel_hi:[1,0]
	v_pk_mul_f32 v[156:157], v[116:117], v[154:155] op_sel_hi:[1,0]
	v_pk_mul_f32 v[158:159], v[118:119], v[154:155] op_sel_hi:[1,0]
	v_pk_mul_f32 v[160:161], v[112:113], v[154:155] op_sel_hi:[1,0]
	v_pk_mul_f32 v[154:155], v[114:115], v[154:155] op_sel_hi:[1,0]
	s_waitcnt vmcnt(3)
	v_pk_mul_f32 v[198:199], v[142:143], v[126:127]
	v_pk_mul_f32 v[196:197], v[140:141], v[124:125]
	s_waitcnt vmcnt(2)
	v_pk_mul_f32 v[202:203], v[138:139], v[122:123]
	v_pk_mul_f32 v[200:201], v[136:137], v[120:121]
	s_waitcnt vmcnt(1)
	v_pk_mul_f32 v[206:207], v[134:135], v[158:159]
	v_pk_mul_f32 v[204:205], v[132:133], v[156:157]
	s_waitcnt vmcnt(0)
	v_pk_mul_f32 v[210:211], v[130:131], v[154:155]
	v_pk_mul_f32 v[208:209], v[128:129], v[160:161]
	global_load_dwordx4 v[112:115], v[152:153], off
	s_nop 0
	global_load_dwordx4 v[116:119], v[152:153], off offset:16
	global_load_dwordx4 v[120:123], v[152:153], off offset:32
	global_load_dwordx4 v[124:127], v[152:153], off offset:48
	global_store_dwordx4 v[150:151], v[196:199], off
	global_store_dwordx4 v[150:151], v[200:203], off offset:16
	global_store_dwordx4 v[150:151], v[204:207], off offset:128
	global_store_dwordx4 v[150:151], v[208:211], off offset:144
	v_or_b32_e32 v150, 32, v146
	v_lshlrev_b64 v[154:155], 12, v[166:167]
	v_lshlrev_b32_e32 v152, 4, v150
	v_ashrrev_i32_e32 v153, 31, v152
	v_ashrrev_i32_e32 v151, 31, v150
	s_waitcnt vmcnt(7)
	v_mov_b32_e32 v156, v113
	v_mov_b32_e32 v157, v114
	v_mov_b32_e32 v113, v115
	s_waitcnt vmcnt(6)
	v_mov_b32_e32 v114, v117
	v_mov_b32_e32 v115, v118
	v_mov_b32_e32 v117, v119
	v_pk_add_f32 v[112:113], v[156:157], v[112:113]
	v_pk_add_f32 v[114:115], v[114:115], v[116:117]
	v_pk_add_f32 v[112:113], v[112:113], v[112:113] op_sel:[0,1] op_sel_hi:[1,0]
	v_pk_add_f32 v[114:115], v[114:115], v[114:115] op_sel:[0,1] op_sel_hi:[1,0]
	s_waitcnt vmcnt(5)
	v_add_f32_e32 v118, v120, v121
	v_add_f32_e32 v120, v122, v123
	s_waitcnt vmcnt(4)
;     __device__ __forceinline__ void after(f32x4 (&acc)[2][2][4][2], const Unit& u, int wr, int wc, int fr, int fq) const {
;     ...
; #pragma unroll
;         for (int ai = 0; ai < 2; ++ai)
; #pragma unroll
;             for (int m = 0; m < 4; ++m) {
;                 const int row = 256 * u.pm + 128 * ai + 64 * wr + 16 * m + fr;
;                 const f32x4* sp = (const f32x4*)(SSQ + row * 16);
;                 const f32x4 s0 = sp[0], s1 = sp[1], s2 = sp[2], s3 = sp[3];
;                 const float tot = ((s0[0] + s0[1]) + (s0[2] + s0[3])) + ((s1[0] + s1[1]) + (s1[2] + s1[3])) + ((s2[0] + s2[1]) + (s2[2] + s2[3])) + ((s3[0] + s3[1]) + (s3[2] + s3[3]));
;                 const float rinv = 1.0f / sqrtf(tot * (1.f / DM) + 1e-6f);
; #pragma unroll
;                 for (int bj = 0; bj < 2; ++bj)
; #pragma unroll
;                     for (int n = 0; n < 2; ++n) {
;                         const int col = 256 * u.pn + 64 * wc + 32 * bj + 8 * fq + 4 * n;
;                         *(f32x4*)(out + (size_t)row * 1024 + col) = acc[ai][bj][m][n] * rinv * gn[bj][n];
;                     }
;             }
	v_mov_b32_e32 v119, v126
	v_mov_b32_e32 v121, v127
	v_mov_b32_e32 v113, v124
	v_mov_b32_e32 v115, v125
	v_pk_add_f32 v[116:117], v[118:119], v[120:121]
	v_pk_add_f32 v[112:113], v[112:113], v[114:115]
	v_lshl_add_u64 v[114:115], v[152:153], 2, s[6:7]
	v_pk_add_f32 v[112:113], v[112:113], v[116:117]
	s_nop 0
	v_add_f32_e32 v112, v112, v113
	v_fmamk_f32 v112, v112, 0x3a800000, v149
	v_mul_f32_e32 v113, 0x4f800000, v112
	v_cmp_gt_f32_e32 vcc, s2, v112
	s_nop 1
	v_cndmask_b32_e32 v116, v112, v113, vcc
	v_sqrt_f32_e32 v117, v116
	v_lshl_add_u64 v[112:113], s[74:75], 0, v[154:155]
	v_lshl_add_u64 v[112:113], v[112:113], 0, v[144:145]
	v_add_u32_e32 v118, -1, v117
	v_add_u32_e32 v119, 1, v117
	v_fma_f32 v120, -v118, v117, v116
	v_fma_f32 v121, -v119, v117, v116
	v_cmp_ge_f32_e64 s[0:1], 0, v120
	s_nop 1
	v_cndmask_b32_e64 v117, v117, v118, s[0:1]
	v_cmp_lt_f32_e64 s[0:1], 0, v121
	s_nop 1
	v_cndmask_b32_e64 v117, v117, v119, s[0:1]
	v_mul_f32_e32 v118, 0x37800000, v117
	v_cndmask_b32_e32 v117, v117, v118, vcc
	v_cmp_class_f32_e32 vcc, v116, v148
	s_nop 1
	v_cndmask_b32_e32 v116, v117, v116, vcc
	v_div_scale_f32 v117, s[0:1], v116, v116, 1.0
	v_rcp_f32_e32 v118, v117
	v_div_scale_f32 v119, vcc, 1.0, v116, 1.0
	v_fma_f32 v120, -v117, v118, 1.0
	v_fmac_f32_e32 v118, v120, v118
	v_mul_f32_e32 v120, v119, v118
	v_fma_f32 v121, -v117, v120, v119
	v_fmac_f32_e32 v120, v121, v118
	v_fma_f32 v117, -v117, v120, v119
	v_div_fmas_f32 v117, v117, v118, v120
	v_div_fixup_f32 v116, v117, v116, 1.0
	v_pk_mul_f32 v[108:109], v[108:109], v[116:117] op_sel_hi:[1,0]
	v_pk_mul_f32 v[110:111], v[110:111], v[116:117] op_sel_hi:[1,0]
	v_pk_mul_f32 v[104:105], v[104:105], v[116:117] op_sel_hi:[1,0]
	v_pk_mul_f32 v[106:107], v[106:107], v[116:117] op_sel_hi:[1,0]
	v_pk_mul_f32 v[118:119], v[100:101], v[116:117] op_sel_hi:[1,0]
	v_pk_mul_f32 v[120:121], v[102:103], v[116:117] op_sel_hi:[1,0]
	v_pk_mul_f32 v[122:123], v[96:97], v[116:117] op_sel_hi:[1,0]
	v_pk_mul_f32 v[116:117], v[98:99], v[116:117] op_sel_hi:[1,0]
	v_pk_mul_f32 v[214:215], v[142:143], v[110:111]
	v_pk_mul_f32 v[212:213], v[140:141], v[108:109]
	v_pk_mul_f32 v[218:219], v[138:139], v[106:107]
	v_pk_mul_f32 v[216:217], v[136:137], v[104:105]
	v_pk_mul_f32 v[222:223], v[134:135], v[120:121]
	v_pk_mul_f32 v[220:221], v[132:133], v[118:119]
	v_pk_mul_f32 v[226:227], v[130:131], v[116:117]
	v_pk_mul_f32 v[224:225], v[128:129], v[122:123]
	global_load_dwordx4 v[96:99], v[114:115], off
	s_nop 0
	global_load_dwordx4 v[100:103], v[114:115], off offset:16
	global_load_dwordx4 v[104:107], v[114:115], off offset:32
	global_load_dwordx4 v[108:111], v[114:115], off offset:48
	global_store_dwordx4 v[112:113], v[212:215], off
	global_store_dwordx4 v[112:113], v[216:219], off offset:16
	global_store_dwordx4 v[112:113], v[220:223], off offset:128
	global_store_dwordx4 v[112:113], v[224:227], off offset:144
	v_or_b32_e32 v112, 48, v146
	v_lshlrev_b64 v[116:117], 12, v[150:151]
	v_lshlrev_b32_e32 v114, 4, v112
	v_ashrrev_i32_e32 v115, 31, v114
	v_ashrrev_i32_e32 v113, 31, v112
	s_waitcnt vmcnt(7)
	v_mov_b32_e32 v118, v97
	v_mov_b32_e32 v119, v98
	v_mov_b32_e32 v97, v99
	s_waitcnt vmcnt(6)
	v_mov_b32_e32 v98, v101
	v_mov_b32_e32 v99, v102
	v_mov_b32_e32 v101, v103
	v_pk_add_f32 v[96:97], v[118:119], v[96:97]
	v_pk_add_f32 v[98:99], v[98:99], v[100:101]
	v_pk_add_f32 v[96:97], v[96:97], v[96:97] op_sel:[0,1] op_sel_hi:[1,0]
	v_pk_add_f32 v[98:99], v[98:99], v[98:99] op_sel:[0,1] op_sel_hi:[1,0]
	s_waitcnt vmcnt(5)
	v_add_f32_e32 v102, v104, v105
	v_add_f32_e32 v104, v106, v107
	s_waitcnt vmcnt(4)
	v_mov_b32_e32 v103, v110
	v_mov_b32_e32 v105, v111
	v_mov_b32_e32 v97, v108
	v_mov_b32_e32 v99, v109
	v_pk_add_f32 v[100:101], v[102:103], v[104:105]
	v_pk_add_f32 v[96:97], v[96:97], v[98:99]
	v_lshl_add_u64 v[98:99], v[114:115], 2, s[6:7]
	v_pk_add_f32 v[96:97], v[96:97], v[100:101]
	s_nop 0
	v_add_f32_e32 v96, v96, v97
	v_fmamk_f32 v96, v96, 0x3a800000, v149
	v_mul_f32_e32 v97, 0x4f800000, v96
	v_cmp_gt_f32_e32 vcc, s2, v96
	s_nop 1
	v_cndmask_b32_e32 v100, v96, v97, vcc
	v_sqrt_f32_e32 v101, v100
	v_lshl_add_u64 v[96:97], s[74:75], 0, v[116:117]
	v_lshl_add_u64 v[96:97], v[96:97], 0, v[144:145]
	v_add_u32_e32 v102, -1, v101
	v_add_u32_e32 v103, 1, v101
	v_fma_f32 v104, -v102, v101, v100
	v_fma_f32 v105, -v103, v101, v100
	v_cmp_ge_f32_e64 s[0:1], 0, v104
	s_nop 1
	v_cndmask_b32_e64 v101, v101, v102, s[0:1]
	v_cmp_lt_f32_e64 s[0:1], 0, v105
	s_nop 1
	v_cndmask_b32_e64 v101, v101, v103, s[0:1]
	v_mul_f32_e32 v102, 0x37800000, v101
	v_cndmask_b32_e32 v101, v101, v102, vcc
	v_cmp_class_f32_e32 vcc, v100, v148
	s_nop 1
	v_cndmask_b32_e32 v100, v101, v100, vcc
	v_div_scale_f32 v101, s[0:1], v100, v100, 1.0
	v_rcp_f32_e32 v102, v101
	v_div_scale_f32 v103, vcc, 1.0, v100, 1.0
	v_fma_f32 v104, -v101, v102, 1.0
	v_fmac_f32_e32 v102, v104, v102
	v_mul_f32_e32 v104, v103, v102
	v_fma_f32 v105, -v101, v104, v103
	v_fmac_f32_e32 v104, v105, v102
	v_fma_f32 v101, -v101, v104, v103
	v_div_fmas_f32 v101, v101, v102, v104
	v_div_fixup_f32 v100, v101, v100, 1.0
	v_pk_mul_f32 v[92:93], v[92:93], v[100:101] op_sel_hi:[1,0]
	v_pk_mul_f32 v[94:95], v[94:95], v[100:101] op_sel_hi:[1,0]
	v_pk_mul_f32 v[88:89], v[88:89], v[100:101] op_sel_hi:[1,0]
	v_pk_mul_f32 v[90:91], v[90:91], v[100:101] op_sel_hi:[1,0]
	v_pk_mul_f32 v[102:103], v[84:85], v[100:101] op_sel_hi:[1,0]
	v_pk_mul_f32 v[104:105], v[86:87], v[100:101] op_sel_hi:[1,0]
	v_pk_mul_f32 v[106:107], v[80:81], v[100:101] op_sel_hi:[1,0]
	v_pk_mul_f32 v[100:101], v[82:83], v[100:101] op_sel_hi:[1,0]
	v_pk_mul_f32 v[198:199], v[142:143], v[94:95]
	v_pk_mul_f32 v[196:197], v[140:141], v[92:93]
	v_pk_mul_f32 v[202:203], v[138:139], v[90:91]
	v_pk_mul_f32 v[200:201], v[136:137], v[88:89]
	v_pk_mul_f32 v[206:207], v[134:135], v[104:105]
	v_pk_mul_f32 v[204:205], v[132:133], v[102:103]
	v_pk_mul_f32 v[210:211], v[130:131], v[100:101]
	v_pk_mul_f32 v[208:209], v[128:129], v[106:107]
	global_load_dwordx4 v[80:83], v[98:99], off
	s_nop 0
	global_load_dwordx4 v[84:87], v[98:99], off offset:16
	global_load_dwordx4 v[88:91], v[98:99], off offset:32
	global_load_dwordx4 v[92:95], v[98:99], off offset:48
	global_store_dwordx4 v[96:97], v[196:199], off
	global_store_dwordx4 v[96:97], v[200:203], off offset:16
	global_store_dwordx4 v[96:97], v[204:207], off offset:128
	global_store_dwordx4 v[96:97], v[208:211], off offset:144
	v_add_u32_e32 v96, 0x80, v146
	v_lshlrev_b64 v[100:101], 12, v[112:113]
	v_lshlrev_b32_e32 v98, 4, v96
	v_ashrrev_i32_e32 v99, 31, v98
	v_ashrrev_i32_e32 v97, 31, v96
	s_waitcnt vmcnt(7)
;     __device__ __forceinline__ void after(f32x4 (&acc)[2][2][4][2], const Unit& u, int wr, int wc, int fr, int fq) const {
;     ...
; #pragma unroll
;         for (int ai = 0; ai < 2; ++ai)
; #pragma unroll
;             for (int m = 0; m < 4; ++m) {
;                 const int row = 256 * u.pm + 128 * ai + 64 * wr + 16 * m + fr;
;                 const f32x4* sp = (const f32x4*)(SSQ + row * 16);
;                 const f32x4 s0 = sp[0], s1 = sp[1], s2 = sp[2], s3 = sp[3];
;                 const float tot = ((s0[0] + s0[1]) + (s0[2] + s0[3])) + ((s1[0] + s1[1]) + (s1[2] + s1[3])) + ((s2[0] + s2[1]) + (s2[2] + s2[3])) + ((s3[0] + s3[1]) + (s3[2] + s3[3]));
;                 const float rinv = 1.0f / sqrtf(tot * (1.f / DM) + 1e-6f);
; #pragma unroll
;                 for (int bj = 0; bj < 2; ++bj)
; #pragma unroll
;                     for (int n = 0; n < 2; ++n) {
;                         const int col = 256 * u.pn + 64 * wc + 32 * bj + 8 * fq + 4 * n;
;                         *(f32x4*)(out + (size_t)row * 1024 + col) = acc[ai][bj][m][n] * rinv * gn[bj][n];
;                     }
;             }
	v_mov_b32_e32 v102, v81
	v_mov_b32_e32 v103, v82
	v_mov_b32_e32 v81, v83
	s_waitcnt vmcnt(6)
	v_mov_b32_e32 v82, v85
	v_mov_b32_e32 v83, v86
	v_mov_b32_e32 v85, v87
	v_pk_add_f32 v[80:81], v[102:103], v[80:81]
	v_pk_add_f32 v[82:83], v[82:83], v[84:85]
	v_pk_add_f32 v[80:81], v[80:81], v[80:81] op_sel:[0,1] op_sel_hi:[1,0]
	v_pk_add_f32 v[82:83], v[82:83], v[82:83] op_sel:[0,1] op_sel_hi:[1,0]
	s_waitcnt vmcnt(5)
	v_add_f32_e32 v86, v88, v89
	v_add_f32_e32 v88, v90, v91
	s_waitcnt vmcnt(4)
	v_mov_b32_e32 v87, v94
	v_mov_b32_e32 v89, v95
	v_mov_b32_e32 v81, v92
	v_mov_b32_e32 v83, v93
	v_pk_add_f32 v[84:85], v[86:87], v[88:89]
	v_pk_add_f32 v[80:81], v[80:81], v[82:83]
	v_lshl_add_u64 v[82:83], v[98:99], 2, s[6:7]
	v_pk_add_f32 v[80:81], v[80:81], v[84:85]
	s_nop 0
	v_add_f32_e32 v80, v80, v81
	v_fmamk_f32 v80, v80, 0x3a800000, v149
	v_mul_f32_e32 v81, 0x4f800000, v80
	v_cmp_gt_f32_e32 vcc, s2, v80
	s_nop 1
	v_cndmask_b32_e32 v84, v80, v81, vcc
	v_sqrt_f32_e32 v85, v84
	v_lshl_add_u64 v[80:81], s[74:75], 0, v[100:101]
	v_lshl_add_u64 v[80:81], v[80:81], 0, v[144:145]
	v_add_u32_e32 v86, -1, v85
	v_add_u32_e32 v87, 1, v85
	v_fma_f32 v88, -v86, v85, v84
	v_fma_f32 v89, -v87, v85, v84
	v_cmp_ge_f32_e64 s[0:1], 0, v88
	s_nop 1
	v_cndmask_b32_e64 v85, v85, v86, s[0:1]
	v_cmp_lt_f32_e64 s[0:1], 0, v89
	s_nop 1
	v_cndmask_b32_e64 v85, v85, v87, s[0:1]
	v_mul_f32_e32 v86, 0x37800000, v85
	v_cndmask_b32_e32 v85, v85, v86, vcc
	v_cmp_class_f32_e32 vcc, v84, v148
	s_nop 1
	v_cndmask_b32_e32 v84, v85, v84, vcc
	v_div_scale_f32 v85, s[0:1], v84, v84, 1.0
	v_rcp_f32_e32 v86, v85
	v_div_scale_f32 v87, vcc, 1.0, v84, 1.0
	v_fma_f32 v88, -v85, v86, 1.0
	v_fmac_f32_e32 v86, v88, v86
	v_mul_f32_e32 v88, v87, v86
	v_fma_f32 v89, -v85, v88, v87
	v_fmac_f32_e32 v88, v89, v86
	v_fma_f32 v85, -v85, v88, v87
	v_div_fmas_f32 v85, v85, v86, v88
	v_div_fixup_f32 v84, v85, v84, 1.0
	v_pk_mul_f32 v[76:77], v[76:77], v[84:85] op_sel_hi:[1,0]
	v_pk_mul_f32 v[78:79], v[78:79], v[84:85] op_sel_hi:[1,0]
	v_pk_mul_f32 v[72:73], v[72:73], v[84:85] op_sel_hi:[1,0]
	v_pk_mul_f32 v[74:75], v[74:75], v[84:85] op_sel_hi:[1,0]
	v_pk_mul_f32 v[86:87], v[68:69], v[84:85] op_sel_hi:[1,0]
	v_pk_mul_f32 v[88:89], v[70:71], v[84:85] op_sel_hi:[1,0]
	v_pk_mul_f32 v[90:91], v[64:65], v[84:85] op_sel_hi:[1,0]
	v_pk_mul_f32 v[84:85], v[66:67], v[84:85] op_sel_hi:[1,0]
	v_pk_mul_f32 v[214:215], v[142:143], v[78:79]
	v_pk_mul_f32 v[212:213], v[140:141], v[76:77]
	v_pk_mul_f32 v[218:219], v[138:139], v[74:75]
	v_pk_mul_f32 v[216:217], v[136:137], v[72:73]
	v_pk_mul_f32 v[222:223], v[134:135], v[88:89]
	v_pk_mul_f32 v[220:221], v[132:133], v[86:87]
	v_pk_mul_f32 v[226:227], v[130:131], v[84:85]
	v_pk_mul_f32 v[224:225], v[128:129], v[90:91]
	global_load_dwordx4 v[64:67], v[82:83], off
	s_nop 0
	global_load_dwordx4 v[68:71], v[82:83], off offset:16
	global_load_dwordx4 v[72:75], v[82:83], off offset:32
	global_load_dwordx4 v[76:79], v[82:83], off offset:48
	global_store_dwordx4 v[80:81], v[212:215], off
	global_store_dwordx4 v[80:81], v[216:219], off offset:16
	global_store_dwordx4 v[80:81], v[220:223], off offset:128
	global_store_dwordx4 v[80:81], v[224:227], off offset:144
	v_add_u32_e32 v80, 0x90, v146
	v_lshlrev_b64 v[84:85], 12, v[96:97]
	v_lshlrev_b32_e32 v82, 4, v80
	v_ashrrev_i32_e32 v83, 31, v82
	v_ashrrev_i32_e32 v81, 31, v80
	s_waitcnt vmcnt(7)
	v_mov_b32_e32 v86, v65
	v_mov_b32_e32 v87, v66
	v_mov_b32_e32 v65, v67
	s_waitcnt vmcnt(6)
	v_mov_b32_e32 v66, v69
	v_mov_b32_e32 v67, v70
	v_mov_b32_e32 v69, v71
	v_pk_add_f32 v[64:65], v[86:87], v[64:65]
	v_pk_add_f32 v[66:67], v[66:67], v[68:69]
	v_pk_add_f32 v[64:65], v[64:65], v[64:65] op_sel:[0,1] op_sel_hi:[1,0]
	v_pk_add_f32 v[66:67], v[66:67], v[66:67] op_sel:[0,1] op_sel_hi:[1,0]
	s_waitcnt vmcnt(5)
	v_add_f32_e32 v70, v72, v73
	v_add_f32_e32 v72, v74, v75
	s_waitcnt vmcnt(4)
	v_mov_b32_e32 v71, v78
	v_mov_b32_e32 v73, v79
	v_mov_b32_e32 v65, v76
	v_mov_b32_e32 v67, v77
	v_pk_add_f32 v[68:69], v[70:71], v[72:73]
	v_pk_add_f32 v[64:65], v[64:65], v[66:67]
	v_lshl_add_u64 v[66:67], v[82:83], 2, s[6:7]
	v_pk_add_f32 v[64:65], v[64:65], v[68:69]
	s_nop 0
	v_add_f32_e32 v64, v64, v65
	v_fmamk_f32 v64, v64, 0x3a800000, v149
	v_mul_f32_e32 v65, 0x4f800000, v64
	v_cmp_gt_f32_e32 vcc, s2, v64
	s_nop 1
	v_cndmask_b32_e32 v68, v64, v65, vcc
	v_sqrt_f32_e32 v69, v68
	v_lshl_add_u64 v[64:65], s[74:75], 0, v[84:85]
	v_lshl_add_u64 v[64:65], v[64:65], 0, v[144:145]
	v_add_u32_e32 v70, -1, v69
	v_add_u32_e32 v71, 1, v69
	v_fma_f32 v72, -v70, v69, v68
	v_fma_f32 v73, -v71, v69, v68
	v_cmp_ge_f32_e64 s[0:1], 0, v72
	s_nop 1
	v_cndmask_b32_e64 v69, v69, v70, s[0:1]
	v_cmp_lt_f32_e64 s[0:1], 0, v73
	s_nop 1
	v_cndmask_b32_e64 v69, v69, v71, s[0:1]
	v_mul_f32_e32 v70, 0x37800000, v69
	v_cndmask_b32_e32 v69, v69, v70, vcc
	v_cmp_class_f32_e32 vcc, v68, v148
	s_nop 1
	v_cndmask_b32_e32 v68, v69, v68, vcc
	v_div_scale_f32 v69, s[0:1], v68, v68, 1.0
	v_rcp_f32_e32 v70, v69
	v_div_scale_f32 v71, vcc, 1.0, v68, 1.0
	v_fma_f32 v72, -v69, v70, 1.0
	v_fmac_f32_e32 v70, v72, v70
	v_mul_f32_e32 v72, v71, v70
	v_fma_f32 v73, -v69, v72, v71
	v_fmac_f32_e32 v72, v73, v70
	v_fma_f32 v69, -v69, v72, v71
	v_div_fmas_f32 v69, v69, v70, v72
	v_div_fixup_f32 v68, v69, v68, 1.0
	v_pk_mul_f32 v[60:61], v[60:61], v[68:69] op_sel_hi:[1,0]
	v_pk_mul_f32 v[62:63], v[62:63], v[68:69] op_sel_hi:[1,0]
	v_pk_mul_f32 v[56:57], v[56:57], v[68:69] op_sel_hi:[1,0]
	v_pk_mul_f32 v[58:59], v[58:59], v[68:69] op_sel_hi:[1,0]
	v_pk_mul_f32 v[70:71], v[52:53], v[68:69] op_sel_hi:[1,0]
	v_pk_mul_f32 v[72:73], v[54:55], v[68:69] op_sel_hi:[1,0]
	v_pk_mul_f32 v[74:75], v[48:49], v[68:69] op_sel_hi:[1,0]
	v_pk_mul_f32 v[68:69], v[50:51], v[68:69] op_sel_hi:[1,0]
	v_pk_mul_f32 v[198:199], v[142:143], v[62:63]
	v_pk_mul_f32 v[196:197], v[140:141], v[60:61]
	v_pk_mul_f32 v[202:203], v[138:139], v[58:59]
	v_pk_mul_f32 v[200:201], v[136:137], v[56:57]
	v_pk_mul_f32 v[206:207], v[134:135], v[72:73]
	v_pk_mul_f32 v[204:205], v[132:133], v[70:71]
	v_pk_mul_f32 v[210:211], v[130:131], v[68:69]
	v_pk_mul_f32 v[208:209], v[128:129], v[74:75]
	global_load_dwordx4 v[48:51], v[66:67], off
	s_nop 0
	global_load_dwordx4 v[52:55], v[66:67], off offset:16
	global_load_dwordx4 v[56:59], v[66:67], off offset:32
	global_load_dwordx4 v[60:63], v[66:67], off offset:48
	global_store_dwordx4 v[64:65], v[196:199], off
	global_store_dwordx4 v[64:65], v[200:203], off offset:16
	global_store_dwordx4 v[64:65], v[204:207], off offset:128
	global_store_dwordx4 v[64:65], v[208:211], off offset:144
	v_add_u32_e32 v64, 0xa0, v146
	v_lshlrev_b64 v[68:69], 12, v[80:81]
	v_lshlrev_b32_e32 v66, 4, v64
	v_ashrrev_i32_e32 v67, 31, v66
	v_ashrrev_i32_e32 v65, 31, v64
	s_waitcnt vmcnt(7)
;     __device__ __forceinline__ void after(f32x4 (&acc)[2][2][4][2], const Unit& u, int wr, int wc, int fr, int fq) const {
;     ...
; #pragma unroll
;         for (int ai = 0; ai < 2; ++ai)
; #pragma unroll
;             for (int m = 0; m < 4; ++m) {
;                 const int row = 256 * u.pm + 128 * ai + 64 * wr + 16 * m + fr;
;                 const f32x4* sp = (const f32x4*)(SSQ + row * 16);
;                 const f32x4 s0 = sp[0], s1 = sp[1], s2 = sp[2], s3 = sp[3];
;                 const float tot = ((s0[0] + s0[1]) + (s0[2] + s0[3])) + ((s1[0] + s1[1]) + (s1[2] + s1[3])) + ((s2[0] + s2[1]) + (s2[2] + s2[3])) + ((s3[0] + s3[1]) + (s3[2] + s3[3]));
;                 const float rinv = 1.0f / sqrtf(tot * (1.f / DM) + 1e-6f);
; #pragma unroll
;                 for (int bj = 0; bj < 2; ++bj)
; #pragma unroll
;                     for (int n = 0; n < 2; ++n) {
;                         const int col = 256 * u.pn + 64 * wc + 32 * bj + 8 * fq + 4 * n;
;                         *(f32x4*)(out + (size_t)row * 1024 + col) = acc[ai][bj][m][n] * rinv * gn[bj][n];
;                     }
;             }
	v_mov_b32_e32 v70, v49
	v_mov_b32_e32 v71, v50
	v_mov_b32_e32 v49, v51
	s_waitcnt vmcnt(6)
	v_mov_b32_e32 v50, v53
	v_mov_b32_e32 v51, v54
	v_mov_b32_e32 v53, v55
	v_pk_add_f32 v[48:49], v[70:71], v[48:49]
	v_pk_add_f32 v[50:51], v[50:51], v[52:53]
	v_pk_add_f32 v[48:49], v[48:49], v[48:49] op_sel:[0,1] op_sel_hi:[1,0]
	v_pk_add_f32 v[50:51], v[50:51], v[50:51] op_sel:[0,1] op_sel_hi:[1,0]
	s_waitcnt vmcnt(5)
	v_add_f32_e32 v54, v56, v57
	v_add_f32_e32 v56, v58, v59
	s_waitcnt vmcnt(4)
	v_mov_b32_e32 v55, v62
	v_mov_b32_e32 v57, v63
	v_mov_b32_e32 v49, v60
	v_mov_b32_e32 v51, v61
	v_pk_add_f32 v[52:53], v[54:55], v[56:57]
	v_pk_add_f32 v[48:49], v[48:49], v[50:51]
	v_lshl_add_u64 v[50:51], v[66:67], 2, s[6:7]
	v_pk_add_f32 v[48:49], v[48:49], v[52:53]
	s_nop 0
	v_add_f32_e32 v48, v48, v49
	v_fmamk_f32 v48, v48, 0x3a800000, v149
	v_mul_f32_e32 v49, 0x4f800000, v48
	v_cmp_gt_f32_e32 vcc, s2, v48
	s_nop 1
	v_cndmask_b32_e32 v52, v48, v49, vcc
	v_sqrt_f32_e32 v53, v52
	v_lshl_add_u64 v[48:49], s[74:75], 0, v[68:69]
	v_lshl_add_u64 v[48:49], v[48:49], 0, v[144:145]
	v_add_u32_e32 v54, -1, v53
	v_add_u32_e32 v55, 1, v53
	v_fma_f32 v56, -v54, v53, v52
	v_fma_f32 v57, -v55, v53, v52
	v_cmp_ge_f32_e64 s[0:1], 0, v56
	s_nop 1
	v_cndmask_b32_e64 v53, v53, v54, s[0:1]
	v_cmp_lt_f32_e64 s[0:1], 0, v57
	s_nop 1
	v_cndmask_b32_e64 v53, v53, v55, s[0:1]
	v_mul_f32_e32 v54, 0x37800000, v53
	v_cndmask_b32_e32 v53, v53, v54, vcc
	v_cmp_class_f32_e32 vcc, v52, v148
	s_nop 1
	v_cndmask_b32_e32 v52, v53, v52, vcc
	v_div_scale_f32 v53, s[0:1], v52, v52, 1.0
	v_rcp_f32_e32 v54, v53
	v_div_scale_f32 v55, vcc, 1.0, v52, 1.0
	v_fma_f32 v56, -v53, v54, 1.0
	v_fmac_f32_e32 v54, v56, v54
	v_mul_f32_e32 v56, v55, v54
	v_fma_f32 v57, -v53, v56, v55
	v_fmac_f32_e32 v56, v57, v54
	v_fma_f32 v53, -v53, v56, v55
	v_div_fmas_f32 v53, v53, v54, v56
	v_div_fixup_f32 v52, v53, v52, 1.0
	v_pk_mul_f32 v[44:45], v[44:45], v[52:53] op_sel_hi:[1,0]
	v_pk_mul_f32 v[46:47], v[46:47], v[52:53] op_sel_hi:[1,0]
	v_pk_mul_f32 v[40:41], v[40:41], v[52:53] op_sel_hi:[1,0]
	v_pk_mul_f32 v[42:43], v[42:43], v[52:53] op_sel_hi:[1,0]
	v_pk_mul_f32 v[54:55], v[36:37], v[52:53] op_sel_hi:[1,0]
	v_pk_mul_f32 v[56:57], v[38:39], v[52:53] op_sel_hi:[1,0]
	v_pk_mul_f32 v[58:59], v[32:33], v[52:53] op_sel_hi:[1,0]
	v_pk_mul_f32 v[52:53], v[34:35], v[52:53] op_sel_hi:[1,0]
	v_pk_mul_f32 v[214:215], v[142:143], v[46:47]
	v_pk_mul_f32 v[212:213], v[140:141], v[44:45]
	v_pk_mul_f32 v[218:219], v[138:139], v[42:43]
	v_pk_mul_f32 v[216:217], v[136:137], v[40:41]
	v_pk_mul_f32 v[222:223], v[134:135], v[56:57]
	v_pk_mul_f32 v[220:221], v[132:133], v[54:55]
	v_pk_mul_f32 v[226:227], v[130:131], v[52:53]
	v_pk_mul_f32 v[224:225], v[128:129], v[58:59]
	global_load_dwordx4 v[32:35], v[50:51], off
	s_nop 0
	global_load_dwordx4 v[36:39], v[50:51], off offset:16
	global_load_dwordx4 v[40:43], v[50:51], off offset:32
	global_load_dwordx4 v[44:47], v[50:51], off offset:48
	global_store_dwordx4 v[48:49], v[212:215], off
	global_store_dwordx4 v[48:49], v[216:219], off offset:16
	global_store_dwordx4 v[48:49], v[220:223], off offset:128
	global_store_dwordx4 v[48:49], v[224:227], off offset:144
	v_add_u32_e32 v48, 0xb0, v146
	v_lshlrev_b64 v[52:53], 12, v[64:65]
	v_lshlrev_b32_e32 v50, 4, v48
	v_ashrrev_i32_e32 v51, 31, v50
	v_ashrrev_i32_e32 v49, 31, v48
	s_waitcnt vmcnt(7)
	v_mov_b32_e32 v54, v33
	v_mov_b32_e32 v55, v34
	v_mov_b32_e32 v33, v35
	s_waitcnt vmcnt(6)
	v_mov_b32_e32 v34, v37
	v_mov_b32_e32 v35, v38
	v_mov_b32_e32 v37, v39
	v_pk_add_f32 v[32:33], v[54:55], v[32:33]
	v_pk_add_f32 v[34:35], v[34:35], v[36:37]
	v_pk_add_f32 v[32:33], v[32:33], v[32:33] op_sel:[0,1] op_sel_hi:[1,0]
	v_pk_add_f32 v[34:35], v[34:35], v[34:35] op_sel:[0,1] op_sel_hi:[1,0]
	s_waitcnt vmcnt(5)
	v_add_f32_e32 v38, v40, v41
	v_add_f32_e32 v40, v42, v43
	s_waitcnt vmcnt(4)
;     __device__ __forceinline__ void after(f32x4 (&acc)[2][2][4][2], const Unit& u, int wr, int wc, int fr, int fq) const {
;     ...
; #pragma unroll
;         for (int ai = 0; ai < 2; ++ai)
; #pragma unroll
;             for (int m = 0; m < 4; ++m) {
;                 const int row = 256 * u.pm + 128 * ai + 64 * wr + 16 * m + fr;
;                 const f32x4* sp = (const f32x4*)(SSQ + row * 16);
;                 const f32x4 s0 = sp[0], s1 = sp[1], s2 = sp[2], s3 = sp[3];
;                 const float tot = ((s0[0] + s0[1]) + (s0[2] + s0[3])) + ((s1[0] + s1[1]) + (s1[2] + s1[3])) + ((s2[0] + s2[1]) + (s2[2] + s2[3])) + ((s3[0] + s3[1]) + (s3[2] + s3[3]));
;                 const float rinv = 1.0f / sqrtf(tot * (1.f / DM) + 1e-6f);
; #pragma unroll
;                 for (int bj = 0; bj < 2; ++bj)
; #pragma unroll
;                     for (int n = 0; n < 2; ++n) {
;                         const int col = 256 * u.pn + 64 * wc + 32 * bj + 8 * fq + 4 * n;
;                         *(f32x4*)(out + (size_t)row * 1024 + col) = acc[ai][bj][m][n] * rinv * gn[bj][n];
;                     }
;             }
	v_mov_b32_e32 v39, v46
	v_mov_b32_e32 v41, v47
	v_mov_b32_e32 v33, v44
	v_mov_b32_e32 v35, v45
	v_pk_add_f32 v[36:37], v[38:39], v[40:41]
	v_pk_add_f32 v[32:33], v[32:33], v[34:35]
	v_lshl_add_u64 v[34:35], v[50:51], 2, s[6:7]
	v_pk_add_f32 v[32:33], v[32:33], v[36:37]
	s_nop 0
	v_add_f32_e32 v32, v32, v33
	v_fmamk_f32 v32, v32, 0x3a800000, v149
	v_mul_f32_e32 v33, 0x4f800000, v32
	v_cmp_gt_f32_e32 vcc, s2, v32
	s_nop 1
	v_cndmask_b32_e32 v36, v32, v33, vcc
	v_sqrt_f32_e32 v37, v36
	v_lshl_add_u64 v[32:33], s[74:75], 0, v[52:53]
	v_lshl_add_u64 v[32:33], v[32:33], 0, v[144:145]
	v_add_u32_e32 v38, -1, v37
	v_add_u32_e32 v39, 1, v37
	v_fma_f32 v40, -v38, v37, v36
	v_fma_f32 v41, -v39, v37, v36
	v_cmp_ge_f32_e64 s[0:1], 0, v40
	s_nop 1
	v_cndmask_b32_e64 v37, v37, v38, s[0:1]
	v_cmp_lt_f32_e64 s[0:1], 0, v41
	s_nop 1
	v_cndmask_b32_e64 v37, v37, v39, s[0:1]
	v_mul_f32_e32 v38, 0x37800000, v37
	v_cndmask_b32_e32 v37, v37, v38, vcc
	v_cmp_class_f32_e32 vcc, v36, v148
	s_nop 1
	v_cndmask_b32_e32 v36, v37, v36, vcc
	v_div_scale_f32 v37, s[0:1], v36, v36, 1.0
	v_rcp_f32_e32 v38, v37
	v_div_scale_f32 v39, vcc, 1.0, v36, 1.0
	v_fma_f32 v40, -v37, v38, 1.0
	v_fmac_f32_e32 v38, v40, v38
	v_mul_f32_e32 v40, v39, v38
	v_fma_f32 v41, -v37, v40, v39
	v_fmac_f32_e32 v40, v41, v38
	v_fma_f32 v37, -v37, v40, v39
	v_div_fmas_f32 v37, v37, v38, v40
	v_div_fixup_f32 v36, v37, v36, 1.0
	v_pk_mul_f32 v[28:29], v[28:29], v[36:37] op_sel_hi:[1,0]
	v_pk_mul_f32 v[30:31], v[30:31], v[36:37] op_sel_hi:[1,0]
	v_pk_mul_f32 v[24:25], v[24:25], v[36:37] op_sel_hi:[1,0]
	v_pk_mul_f32 v[26:27], v[26:27], v[36:37] op_sel_hi:[1,0]
	v_pk_mul_f32 v[38:39], v[20:21], v[36:37] op_sel_hi:[1,0]
	v_pk_mul_f32 v[40:41], v[22:23], v[36:37] op_sel_hi:[1,0]
	v_pk_mul_f32 v[42:43], v[16:17], v[36:37] op_sel_hi:[1,0]
	v_pk_mul_f32 v[36:37], v[18:19], v[36:37] op_sel_hi:[1,0]
	v_pk_mul_f32 v[198:199], v[142:143], v[30:31]
	v_pk_mul_f32 v[196:197], v[140:141], v[28:29]
	v_pk_mul_f32 v[202:203], v[138:139], v[26:27]
	v_pk_mul_f32 v[200:201], v[136:137], v[24:25]
	v_pk_mul_f32 v[206:207], v[134:135], v[40:41]
	v_pk_mul_f32 v[204:205], v[132:133], v[38:39]
	v_pk_mul_f32 v[210:211], v[130:131], v[36:37]
	v_pk_mul_f32 v[208:209], v[128:129], v[42:43]
	global_load_dwordx4 v[16:19], v[34:35], off
	s_nop 0
	global_load_dwordx4 v[20:23], v[34:35], off offset:16
	global_load_dwordx4 v[24:27], v[34:35], off offset:32
	global_load_dwordx4 v[28:31], v[34:35], off offset:48
	global_store_dwordx4 v[32:33], v[196:199], off
	global_store_dwordx4 v[32:33], v[200:203], off offset:16
	global_store_dwordx4 v[32:33], v[204:207], off offset:128
	global_store_dwordx4 v[32:33], v[208:211], off offset:144
	s_waitcnt vmcnt(7)
	v_mov_b32_e32 v32, v17
	v_mov_b32_e32 v33, v18
	v_mov_b32_e32 v17, v19
	s_waitcnt vmcnt(6)
	v_mov_b32_e32 v18, v21
	v_mov_b32_e32 v19, v22
	v_mov_b32_e32 v21, v23
	v_pk_add_f32 v[16:17], v[32:33], v[16:17]
	v_pk_add_f32 v[18:19], v[18:19], v[20:21]
	v_pk_add_f32 v[16:17], v[16:17], v[16:17] op_sel:[0,1] op_sel_hi:[1,0]
	v_pk_add_f32 v[18:19], v[18:19], v[18:19] op_sel:[0,1] op_sel_hi:[1,0]
	s_waitcnt vmcnt(5)
	v_add_f32_e32 v22, v24, v25
	v_add_f32_e32 v24, v26, v27
	s_waitcnt vmcnt(4)
	v_mov_b32_e32 v23, v30
	v_mov_b32_e32 v25, v31
	v_mov_b32_e32 v17, v28
	v_mov_b32_e32 v19, v29
	v_pk_add_f32 v[20:21], v[22:23], v[24:25]
	v_pk_add_f32 v[16:17], v[16:17], v[18:19]
	s_nop 0
	v_pk_add_f32 v[16:17], v[16:17], v[20:21]
	s_nop 0
	v_add_f32_e32 v16, v16, v17
	v_fmac_f32_e32 v149, 0x3a800000, v16
	v_mul_f32_e32 v16, 0x4f800000, v149
	v_cmp_gt_f32_e32 vcc, s2, v149
	s_nop 1
	v_cndmask_b32_e32 v18, v149, v16, vcc
	v_sqrt_f32_e32 v19, v18
	v_lshlrev_b64 v[16:17], 12, v[48:49]
	v_lshl_add_u64 v[16:17], s[74:75], 0, v[16:17]
	v_lshl_add_u64 v[16:17], v[16:17], 0, v[144:145]
	v_add_u32_e32 v20, -1, v19
	v_add_u32_e32 v21, 1, v19
	v_fma_f32 v22, -v20, v19, v18
	v_fma_f32 v23, -v21, v19, v18
	v_cmp_ge_f32_e64 s[0:1], 0, v22
	s_nop 1
	v_cndmask_b32_e64 v19, v19, v20, s[0:1]
	v_cmp_lt_f32_e64 s[0:1], 0, v23
	s_nop 1
	v_cndmask_b32_e64 v19, v19, v21, s[0:1]
	v_mul_f32_e32 v20, 0x37800000, v19
	v_cndmask_b32_e32 v19, v19, v20, vcc
	v_cmp_class_f32_e32 vcc, v18, v148
	s_nop 1
	v_cndmask_b32_e32 v18, v19, v18, vcc
	v_div_scale_f32 v19, s[0:1], v18, v18, 1.0
	v_rcp_f32_e32 v20, v19
	v_div_scale_f32 v21, vcc, 1.0, v18, 1.0
	v_fma_f32 v22, -v19, v20, 1.0
	v_fmac_f32_e32 v20, v22, v20
	v_mul_f32_e32 v22, v21, v20
	v_fma_f32 v23, -v19, v22, v21
	v_fmac_f32_e32 v22, v23, v20
	v_fma_f32 v19, -v19, v22, v21
	v_div_fmas_f32 v19, v19, v20, v22
	v_div_fixup_f32 v18, v19, v18, 1.0
	v_pk_mul_f32 v[12:13], v[12:13], v[18:19] op_sel_hi:[1,0]
	v_pk_mul_f32 v[14:15], v[14:15], v[18:19] op_sel_hi:[1,0]
	v_pk_mul_f32 v[8:9], v[8:9], v[18:19] op_sel_hi:[1,0]
	v_pk_mul_f32 v[10:11], v[10:11], v[18:19] op_sel_hi:[1,0]
	v_pk_mul_f32 v[20:21], v[4:5], v[18:19] op_sel_hi:[1,0]
	v_pk_mul_f32 v[22:23], v[6:7], v[18:19] op_sel_hi:[1,0]
	v_pk_mul_f32 v[24:25], v[0:1], v[18:19] op_sel_hi:[1,0]
	v_pk_mul_f32 v[18:19], v[2:3], v[18:19] op_sel_hi:[1,0]
	v_pk_mul_f32 v[2:3], v[142:143], v[14:15]
	v_pk_mul_f32 v[0:1], v[140:141], v[12:13]
	v_pk_mul_f32 v[6:7], v[138:139], v[10:11]
	v_pk_mul_f32 v[4:5], v[136:137], v[8:9]
	v_pk_mul_f32 v[10:11], v[134:135], v[22:23]
	v_pk_mul_f32 v[8:9], v[132:133], v[20:21]
	v_pk_mul_f32 v[14:15], v[130:131], v[18:19]
	v_pk_mul_f32 v[12:13], v[128:129], v[24:25]
	global_store_dwordx4 v[16:17], v[0:3], off
	global_store_dwordx4 v[16:17], v[4:7], off offset:16
	global_store_dwordx4 v[16:17], v[8:11], off offset:128
	global_store_dwordx4 v[16:17], v[12:15], off offset:144
	s_endpgm
